# residual-add GEMM epilogues: 16 base loads in flight per half tile instead of one exposed round trip per 8 outputs
# speedup vs baseline: 1.0087x; 1.0087x over previous
;     __device__ __forceinline__ void operator()(const f32x4 (&acc)[2][2][4][2], const Unit& u, int wr, int wc, int fr, int fq) const {
;         const int row0 = u.pm * BM + wr * 64 + fr, col0 = u.pn * BM + wc * 32 + 8 * fq;
; #pragma unroll
;         for (int ai = 0; ai < 2; ++ai)
; #pragma unroll
;             for (int m = 0; m < 4; ++m) { const size_t ro = (size_t)(row0 + ai * HALF + m * 16) * ldc + col0;
; #pragma unroll
;                 for (int bj = 0; bj < 2; ++bj) {
;                     const f32x4 b0 = *(const f32x4*)(base + ro + bj * HALF), b1 = *(const f32x4*)(base + ro + bj * HALF + 4);
;                     *(f32x4*)(out + ro + bj * HALF) = b0 + acc[ai][bj][m][0] * scale;
;                     *(f32x4*)(out + ro + bj * HALF + 4) = b1 + acc[ai][bj][m][1] * scale; } }
;     }
.LBB0_182:
	v_lshl_add_u32 v219, s68, 8, v146
	v_lshl_or_b32 v220, s69, 8, v148
	v_lshlrev_b32_e32 v219, 13, v219
	v_lshl_add_u32 v218, v220, 2, v219
	s_and_b64 vcc, exec, s[4:5]
	s_mov_b64 s[4:5], -1
	v_add_u32_e32 v219, 0x0, v218
	global_load_dwordx4 v[152:155], v219, s[16:17]
	global_load_dwordx4 v[156:159], v219, s[16:17] offset:16
	global_load_dwordx4 v[160:163], v219, s[16:17] offset:512
	global_load_dwordx4 v[164:167], v219, s[16:17] offset:528
	v_add_u32_e32 v220, 0x20000, v218
	global_load_dwordx4 v[168:171], v220, s[16:17]
	global_load_dwordx4 v[172:175], v220, s[16:17] offset:16
	global_load_dwordx4 v[176:179], v220, s[16:17] offset:512
	global_load_dwordx4 v[180:183], v220, s[16:17] offset:528
	v_add_u32_e32 v219, 0x40000, v218
	global_load_dwordx4 v[186:189], v219, s[16:17]
	global_load_dwordx4 v[190:193], v219, s[16:17] offset:16
	global_load_dwordx4 v[194:197], v219, s[16:17] offset:512
	global_load_dwordx4 v[198:201], v219, s[16:17] offset:528
	v_add_u32_e32 v220, 0x60000, v218
	global_load_dwordx4 v[202:205], v220, s[16:17]
	global_load_dwordx4 v[206:209], v220, s[16:17] offset:16
	global_load_dwordx4 v[210:213], v220, s[16:17] offset:512
	global_load_dwordx4 v[214:217], v220, s[16:17] offset:528
	s_waitcnt vmcnt(15)
	v_pk_fma_f32 v[124:125], v[124:125], 0.5, v[152:153] op_sel_hi:[1,0,1]
	v_pk_fma_f32 v[126:127], v[126:127], 0.5, v[154:155] op_sel_hi:[1,0,1]
	s_waitcnt vmcnt(14)
	v_pk_fma_f32 v[120:121], v[120:121], 0.5, v[156:157] op_sel_hi:[1,0,1]
	v_pk_fma_f32 v[122:123], v[122:123], 0.5, v[158:159] op_sel_hi:[1,0,1]
	s_waitcnt vmcnt(13)
	v_pk_fma_f32 v[112:113], v[112:113], 0.5, v[160:161] op_sel_hi:[1,0,1]
	v_pk_fma_f32 v[114:115], v[114:115], 0.5, v[162:163] op_sel_hi:[1,0,1]
	s_waitcnt vmcnt(12)
	v_pk_fma_f32 v[108:109], v[108:109], 0.5, v[164:165] op_sel_hi:[1,0,1]
	v_pk_fma_f32 v[110:111], v[110:111], 0.5, v[166:167] op_sel_hi:[1,0,1]
	s_waitcnt vmcnt(11)
	v_pk_fma_f32 v[116:117], v[116:117], 0.5, v[168:169] op_sel_hi:[1,0,1]
	v_pk_fma_f32 v[118:119], v[118:119], 0.5, v[170:171] op_sel_hi:[1,0,1]
	s_waitcnt vmcnt(10)
	v_pk_fma_f32 v[104:105], v[104:105], 0.5, v[172:173] op_sel_hi:[1,0,1]
	v_pk_fma_f32 v[106:107], v[106:107], 0.5, v[174:175] op_sel_hi:[1,0,1]
	s_waitcnt vmcnt(9)
	v_pk_fma_f32 v[96:97], v[96:97], 0.5, v[176:177] op_sel_hi:[1,0,1]
	v_pk_fma_f32 v[98:99], v[98:99], 0.5, v[178:179] op_sel_hi:[1,0,1]
	s_waitcnt vmcnt(8)
	v_pk_fma_f32 v[92:93], v[92:93], 0.5, v[180:181] op_sel_hi:[1,0,1]
	v_pk_fma_f32 v[94:95], v[94:95], 0.5, v[182:183] op_sel_hi:[1,0,1]
	s_waitcnt vmcnt(7)
	v_pk_fma_f32 v[100:101], v[100:101], 0.5, v[186:187] op_sel_hi:[1,0,1]
	v_pk_fma_f32 v[102:103], v[102:103], 0.5, v[188:189] op_sel_hi:[1,0,1]
	s_waitcnt vmcnt(6)
	v_pk_fma_f32 v[88:89], v[88:89], 0.5, v[190:191] op_sel_hi:[1,0,1]
	v_pk_fma_f32 v[90:91], v[90:91], 0.5, v[192:193] op_sel_hi:[1,0,1]
	s_waitcnt vmcnt(5)
	v_pk_fma_f32 v[80:81], v[80:81], 0.5, v[194:195] op_sel_hi:[1,0,1]
	v_pk_fma_f32 v[82:83], v[82:83], 0.5, v[196:197] op_sel_hi:[1,0,1]
	s_waitcnt vmcnt(4)
	v_pk_fma_f32 v[76:77], v[76:77], 0.5, v[198:199] op_sel_hi:[1,0,1]
	v_pk_fma_f32 v[78:79], v[78:79], 0.5, v[200:201] op_sel_hi:[1,0,1]
	s_waitcnt vmcnt(3)
	v_pk_fma_f32 v[84:85], v[84:85], 0.5, v[202:203] op_sel_hi:[1,0,1]
	v_pk_fma_f32 v[86:87], v[86:87], 0.5, v[204:205] op_sel_hi:[1,0,1]
	s_waitcnt vmcnt(2)
	v_pk_fma_f32 v[72:73], v[72:73], 0.5, v[206:207] op_sel_hi:[1,0,1]
	v_pk_fma_f32 v[74:75], v[74:75], 0.5, v[208:209] op_sel_hi:[1,0,1]
	s_waitcnt vmcnt(1)
	v_pk_fma_f32 v[68:69], v[68:69], 0.5, v[210:211] op_sel_hi:[1,0,1]
	v_pk_fma_f32 v[70:71], v[70:71], 0.5, v[212:213] op_sel_hi:[1,0,1]
	s_waitcnt vmcnt(0)
;     __device__ __forceinline__ void operator()(const f32x4 (&acc)[2][2][4][2], const Unit& u, int wr, int wc, int fr, int fq) const {
;         const int row0 = u.pm * BM + wr * 64 + fr, col0 = u.pn * BM + wc * 32 + 8 * fq;
; #pragma unroll
;         for (int ai = 0; ai < 2; ++ai)
; #pragma unroll
;             for (int m = 0; m < 4; ++m) { const size_t ro = (size_t)(row0 + ai * HALF + m * 16) * ldc + col0;
; #pragma unroll
;                 for (int bj = 0; bj < 2; ++bj) {
;                     const f32x4 b0 = *(const f32x4*)(base + ro + bj * HALF), b1 = *(const f32x4*)(base + ro + bj * HALF + 4);
;                     *(f32x4*)(out + ro + bj * HALF) = b0 + acc[ai][bj][m][0] * scale;
;                     *(f32x4*)(out + ro + bj * HALF + 4) = b1 + acc[ai][bj][m][1] * scale; } }
;     }
	v_pk_fma_f32 v[64:65], v[64:65], 0.5, v[214:215] op_sel_hi:[1,0,1]
	v_pk_fma_f32 v[66:67], v[66:67], 0.5, v[216:217] op_sel_hi:[1,0,1]
	v_add_u32_e32 v219, 0x100000, v218
	global_load_dwordx4 v[152:155], v219, s[16:17]
	global_load_dwordx4 v[156:159], v219, s[16:17] offset:16
	global_load_dwordx4 v[160:163], v219, s[16:17] offset:512
	global_load_dwordx4 v[164:167], v219, s[16:17] offset:528
	v_add_u32_e32 v220, 0x120000, v218
	global_load_dwordx4 v[168:171], v220, s[16:17]
	global_load_dwordx4 v[172:175], v220, s[16:17] offset:16
	global_load_dwordx4 v[176:179], v220, s[16:17] offset:512
	global_load_dwordx4 v[180:183], v220, s[16:17] offset:528
	v_add_u32_e32 v219, 0x140000, v218
	global_load_dwordx4 v[186:189], v219, s[16:17]
	global_load_dwordx4 v[190:193], v219, s[16:17] offset:16
	global_load_dwordx4 v[194:197], v219, s[16:17] offset:512
	global_load_dwordx4 v[198:201], v219, s[16:17] offset:528
	v_add_u32_e32 v220, 0x160000, v218
	global_load_dwordx4 v[202:205], v220, s[16:17]
	global_load_dwordx4 v[206:209], v220, s[16:17] offset:16
	global_load_dwordx4 v[210:213], v220, s[16:17] offset:512
	global_load_dwordx4 v[214:217], v220, s[16:17] offset:528
	v_add_u32_e32 v219, 0x0, v218
	global_store_dwordx4 v219, v[124:127], s[18:19]
	global_store_dwordx4 v219, v[120:123], s[18:19] offset:16
	global_store_dwordx4 v219, v[112:115], s[18:19] offset:512
	global_store_dwordx4 v219, v[108:111], s[18:19] offset:528
	v_add_u32_e32 v220, 0x20000, v218
	global_store_dwordx4 v220, v[116:119], s[18:19]
	global_store_dwordx4 v220, v[104:107], s[18:19] offset:16
	global_store_dwordx4 v220, v[96:99], s[18:19] offset:512
	global_store_dwordx4 v220, v[92:95], s[18:19] offset:528
	v_add_u32_e32 v219, 0x40000, v218
	global_store_dwordx4 v219, v[100:103], s[18:19]
	global_store_dwordx4 v219, v[88:91], s[18:19] offset:16
	global_store_dwordx4 v219, v[80:83], s[18:19] offset:512
	global_store_dwordx4 v219, v[76:79], s[18:19] offset:528
	v_add_u32_e32 v220, 0x60000, v218
	global_store_dwordx4 v220, v[84:87], s[18:19]
	global_store_dwordx4 v220, v[72:75], s[18:19] offset:16
	global_store_dwordx4 v220, v[68:71], s[18:19] offset:512
	global_store_dwordx4 v220, v[64:67], s[18:19] offset:528
	s_waitcnt vmcnt(31)
	v_pk_fma_f32 v[60:61], v[60:61], 0.5, v[152:153] op_sel_hi:[1,0,1]
	v_pk_fma_f32 v[62:63], v[62:63], 0.5, v[154:155] op_sel_hi:[1,0,1]
	s_waitcnt vmcnt(30)
	v_pk_fma_f32 v[56:57], v[56:57], 0.5, v[156:157] op_sel_hi:[1,0,1]
	v_pk_fma_f32 v[58:59], v[58:59], 0.5, v[158:159] op_sel_hi:[1,0,1]
	s_waitcnt vmcnt(29)
	v_pk_fma_f32 v[48:49], v[48:49], 0.5, v[160:161] op_sel_hi:[1,0,1]
	v_pk_fma_f32 v[50:51], v[50:51], 0.5, v[162:163] op_sel_hi:[1,0,1]
	s_waitcnt vmcnt(28)
	v_pk_fma_f32 v[44:45], v[44:45], 0.5, v[164:165] op_sel_hi:[1,0,1]
	v_pk_fma_f32 v[46:47], v[46:47], 0.5, v[166:167] op_sel_hi:[1,0,1]
	s_waitcnt vmcnt(27)
	v_pk_fma_f32 v[52:53], v[52:53], 0.5, v[168:169] op_sel_hi:[1,0,1]
	v_pk_fma_f32 v[54:55], v[54:55], 0.5, v[170:171] op_sel_hi:[1,0,1]
	s_waitcnt vmcnt(26)
	v_pk_fma_f32 v[40:41], v[40:41], 0.5, v[172:173] op_sel_hi:[1,0,1]
	v_pk_fma_f32 v[42:43], v[42:43], 0.5, v[174:175] op_sel_hi:[1,0,1]
	s_waitcnt vmcnt(25)
	v_pk_fma_f32 v[32:33], v[32:33], 0.5, v[176:177] op_sel_hi:[1,0,1]
	v_pk_fma_f32 v[34:35], v[34:35], 0.5, v[178:179] op_sel_hi:[1,0,1]
	s_waitcnt vmcnt(24)
	v_pk_fma_f32 v[28:29], v[28:29], 0.5, v[180:181] op_sel_hi:[1,0,1]
	v_pk_fma_f32 v[30:31], v[30:31], 0.5, v[182:183] op_sel_hi:[1,0,1]
	s_waitcnt vmcnt(23)
	v_pk_fma_f32 v[36:37], v[36:37], 0.5, v[186:187] op_sel_hi:[1,0,1]
	v_pk_fma_f32 v[38:39], v[38:39], 0.5, v[188:189] op_sel_hi:[1,0,1]
	s_waitcnt vmcnt(22)
	v_pk_fma_f32 v[24:25], v[24:25], 0.5, v[190:191] op_sel_hi:[1,0,1]
	v_pk_fma_f32 v[26:27], v[26:27], 0.5, v[192:193] op_sel_hi:[1,0,1]
	s_waitcnt vmcnt(21)
	v_pk_fma_f32 v[16:17], v[16:17], 0.5, v[194:195] op_sel_hi:[1,0,1]
	v_pk_fma_f32 v[18:19], v[18:19], 0.5, v[196:197] op_sel_hi:[1,0,1]
	s_waitcnt vmcnt(20)
	v_pk_fma_f32 v[12:13], v[12:13], 0.5, v[198:199] op_sel_hi:[1,0,1]
	v_pk_fma_f32 v[14:15], v[14:15], 0.5, v[200:201] op_sel_hi:[1,0,1]
	s_waitcnt vmcnt(19)
	v_pk_fma_f32 v[20:21], v[20:21], 0.5, v[202:203] op_sel_hi:[1,0,1]
	v_pk_fma_f32 v[22:23], v[22:23], 0.5, v[204:205] op_sel_hi:[1,0,1]
	s_waitcnt vmcnt(18)
	v_pk_fma_f32 v[8:9], v[8:9], 0.5, v[206:207] op_sel_hi:[1,0,1]
	v_pk_fma_f32 v[10:11], v[10:11], 0.5, v[208:209] op_sel_hi:[1,0,1]
	s_waitcnt vmcnt(17)
	v_pk_fma_f32 v[4:5], v[4:5], 0.5, v[210:211] op_sel_hi:[1,0,1]
	v_pk_fma_f32 v[6:7], v[6:7], 0.5, v[212:213] op_sel_hi:[1,0,1]
	s_waitcnt vmcnt(16)
	v_pk_fma_f32 v[0:1], v[0:1], 0.5, v[214:215] op_sel_hi:[1,0,1]
	v_pk_fma_f32 v[2:3], v[2:3], 0.5, v[216:217] op_sel_hi:[1,0,1]
	v_add_u32_e32 v219, 0x100000, v218
	global_store_dwordx4 v219, v[60:63], s[18:19]
	global_store_dwordx4 v219, v[56:59], s[18:19] offset:16
	global_store_dwordx4 v219, v[48:51], s[18:19] offset:512
	global_store_dwordx4 v219, v[44:47], s[18:19] offset:528
	v_add_u32_e32 v220, 0x120000, v218
	global_store_dwordx4 v220, v[52:55], s[18:19]
	global_store_dwordx4 v220, v[40:43], s[18:19] offset:16
	global_store_dwordx4 v220, v[32:35], s[18:19] offset:512
	global_store_dwordx4 v220, v[28:31], s[18:19] offset:528
	v_add_u32_e32 v219, 0x140000, v218
	global_store_dwordx4 v219, v[36:39], s[18:19]
	global_store_dwordx4 v219, v[24:27], s[18:19] offset:16
	global_store_dwordx4 v219, v[16:19], s[18:19] offset:512
	global_store_dwordx4 v219, v[12:15], s[18:19] offset:528
	v_add_u32_e32 v220, 0x160000, v218
	global_store_dwordx4 v220, v[20:23], s[18:19]
	global_store_dwordx4 v220, v[8:11], s[18:19] offset:16
	global_store_dwordx4 v220, v[4:7], s[18:19] offset:512
	global_store_dwordx4 v220, v[0:3], s[18:19] offset:528
	s_nop 1
	s_cbranch_vccnz .LBB0_167
	s_andn2_b64 vcc, exec, s[12:13]
	s_cbranch_vccnz .LBB0_166
	s_barrier
	s_branch .LBB0_166

;     __device__ __forceinline__ void operator()(const f32x4 (&acc)[2][2][4][2], const Unit& u, int wr, int wc, int fr, int fq) const {
;         const int row0 = u.pm * BM + wr * 64 + fr, col0 = u.pn * BM + wc * 32 + 8 * fq;
; #pragma unroll
;         for (int ai = 0; ai < 2; ++ai)
; #pragma unroll
;             for (int m = 0; m < 4; ++m) { const size_t ro = (size_t)(row0 + ai * HALF + m * 16) * ldc + col0;
; #pragma unroll
;                 for (int bj = 0; bj < 2; ++bj) {
;                     const f32x4 b0 = *(const f32x4*)(base + ro + bj * HALF), b1 = *(const f32x4*)(base + ro + bj * HALF + 4);
;                     *(f32x4*)(out + ro + bj * HALF) = b0 + acc[ai][bj][m][0] * scale;
;                     *(f32x4*)(out + ro + bj * HALF + 4) = b1 + acc[ai][bj][m][1] * scale; } }
.LBB0_1324:
	v_lshl_add_u32 v219, s50, 8, v150
	v_lshl_or_b32 v220, s51, 8, v152
	v_lshlrev_b32_e32 v219, 13, v219
	v_lshl_add_u32 v218, v220, 2, v219
	s_mov_b64 s[50:51], -1
	s_andn2_b64 vcc, exec, s[4:5]
	v_add_u32_e32 v219, 0x0, v218
	global_load_dwordx4 v[144:147], v219, s[12:13]
	global_load_dwordx4 v[156:159], v219, s[12:13] offset:16
	global_load_dwordx4 v[160:163], v219, s[12:13] offset:512
	global_load_dwordx4 v[164:167], v219, s[12:13] offset:528
	v_add_u32_e32 v220, 0x20000, v218
	global_load_dwordx4 v[168:171], v220, s[12:13]
	global_load_dwordx4 v[172:175], v220, s[12:13] offset:16
	global_load_dwordx4 v[176:179], v220, s[12:13] offset:512
	global_load_dwordx4 v[180:183], v220, s[12:13] offset:528
	v_add_u32_e32 v219, 0x40000, v218
	global_load_dwordx4 v[186:189], v219, s[12:13]
	global_load_dwordx4 v[190:193], v219, s[12:13] offset:16
	global_load_dwordx4 v[194:197], v219, s[12:13] offset:512
	global_load_dwordx4 v[198:201], v219, s[12:13] offset:528
	v_add_u32_e32 v220, 0x60000, v218
	global_load_dwordx4 v[202:205], v220, s[12:13]
	global_load_dwordx4 v[206:209], v220, s[12:13] offset:16
	global_load_dwordx4 v[210:213], v220, s[12:13] offset:512
	global_load_dwordx4 v[214:217], v220, s[12:13] offset:528
	s_waitcnt vmcnt(15)
	v_pk_add_f32 v[124:125], v[124:125], v[144:145]
	v_pk_add_f32 v[126:127], v[126:127], v[146:147]
	s_waitcnt vmcnt(14)
	v_pk_add_f32 v[120:121], v[120:121], v[156:157]
	v_pk_add_f32 v[122:123], v[122:123], v[158:159]
	s_waitcnt vmcnt(13)
	v_pk_add_f32 v[116:117], v[116:117], v[160:161]
	v_pk_add_f32 v[118:119], v[118:119], v[162:163]
	s_waitcnt vmcnt(12)
	v_pk_add_f32 v[112:113], v[112:113], v[164:165]
	v_pk_add_f32 v[114:115], v[114:115], v[166:167]
	s_waitcnt vmcnt(11)
	v_pk_add_f32 v[108:109], v[108:109], v[168:169]
	v_pk_add_f32 v[110:111], v[110:111], v[170:171]
	s_waitcnt vmcnt(10)
	v_pk_add_f32 v[104:105], v[104:105], v[172:173]
	v_pk_add_f32 v[106:107], v[106:107], v[174:175]
	s_waitcnt vmcnt(9)
	v_pk_add_f32 v[100:101], v[100:101], v[176:177]
	v_pk_add_f32 v[102:103], v[102:103], v[178:179]
	s_waitcnt vmcnt(8)
	v_pk_add_f32 v[96:97], v[96:97], v[180:181]
	v_pk_add_f32 v[98:99], v[98:99], v[182:183]
	s_waitcnt vmcnt(7)
	v_pk_add_f32 v[92:93], v[92:93], v[186:187]
	v_pk_add_f32 v[94:95], v[94:95], v[188:189]
	s_waitcnt vmcnt(6)
	v_pk_add_f32 v[88:89], v[88:89], v[190:191]
	v_pk_add_f32 v[90:91], v[90:91], v[192:193]
	s_waitcnt vmcnt(5)
	v_pk_add_f32 v[84:85], v[84:85], v[194:195]
	v_pk_add_f32 v[86:87], v[86:87], v[196:197]
	s_waitcnt vmcnt(4)
	v_pk_add_f32 v[80:81], v[80:81], v[198:199]
	v_pk_add_f32 v[82:83], v[82:83], v[200:201]
	s_waitcnt vmcnt(3)
	v_pk_add_f32 v[76:77], v[76:77], v[202:203]
	v_pk_add_f32 v[78:79], v[78:79], v[204:205]
	s_waitcnt vmcnt(2)
	v_pk_add_f32 v[72:73], v[72:73], v[206:207]
	v_pk_add_f32 v[74:75], v[74:75], v[208:209]
	s_waitcnt vmcnt(1)
	v_pk_add_f32 v[68:69], v[68:69], v[210:211]
	v_pk_add_f32 v[70:71], v[70:71], v[212:213]
	s_waitcnt vmcnt(0)
;     __device__ __forceinline__ void operator()(const f32x4 (&acc)[2][2][4][2], const Unit& u, int wr, int wc, int fr, int fq) const {
;         const int row0 = u.pm * BM + wr * 64 + fr, col0 = u.pn * BM + wc * 32 + 8 * fq;
; #pragma unroll
;         for (int ai = 0; ai < 2; ++ai)
; #pragma unroll
;             for (int m = 0; m < 4; ++m) { const size_t ro = (size_t)(row0 + ai * HALF + m * 16) * ldc + col0;
; #pragma unroll
;                 for (int bj = 0; bj < 2; ++bj) {
;                     const f32x4 b0 = *(const f32x4*)(base + ro + bj * HALF), b1 = *(const f32x4*)(base + ro + bj * HALF + 4);
;                     *(f32x4*)(out + ro + bj * HALF) = b0 + acc[ai][bj][m][0] * scale;
;                     *(f32x4*)(out + ro + bj * HALF + 4) = b1 + acc[ai][bj][m][1] * scale; } }
	v_pk_add_f32 v[64:65], v[64:65], v[214:215]
	v_pk_add_f32 v[66:67], v[66:67], v[216:217]
	v_add_u32_e32 v219, 0x100000, v218
	global_load_dwordx4 v[144:147], v219, s[12:13]
	global_load_dwordx4 v[156:159], v219, s[12:13] offset:16
	global_load_dwordx4 v[160:163], v219, s[12:13] offset:512
	global_load_dwordx4 v[164:167], v219, s[12:13] offset:528
	v_add_u32_e32 v220, 0x120000, v218
	global_load_dwordx4 v[168:171], v220, s[12:13]
	global_load_dwordx4 v[172:175], v220, s[12:13] offset:16
	global_load_dwordx4 v[176:179], v220, s[12:13] offset:512
	global_load_dwordx4 v[180:183], v220, s[12:13] offset:528
	v_add_u32_e32 v219, 0x140000, v218
	global_load_dwordx4 v[186:189], v219, s[12:13]
	global_load_dwordx4 v[190:193], v219, s[12:13] offset:16
	global_load_dwordx4 v[194:197], v219, s[12:13] offset:512
	global_load_dwordx4 v[198:201], v219, s[12:13] offset:528
	v_add_u32_e32 v220, 0x160000, v218
	global_load_dwordx4 v[202:205], v220, s[12:13]
	global_load_dwordx4 v[206:209], v220, s[12:13] offset:16
	global_load_dwordx4 v[210:213], v220, s[12:13] offset:512
	global_load_dwordx4 v[214:217], v220, s[12:13] offset:528
	v_add_u32_e32 v219, 0x0, v218
	global_store_dwordx4 v219, v[124:127], s[12:13]
	global_store_dwordx4 v219, v[120:123], s[12:13] offset:16
	global_store_dwordx4 v219, v[116:119], s[12:13] offset:512
	global_store_dwordx4 v219, v[112:115], s[12:13] offset:528
	v_add_u32_e32 v220, 0x20000, v218
	global_store_dwordx4 v220, v[108:111], s[12:13]
	global_store_dwordx4 v220, v[104:107], s[12:13] offset:16
	global_store_dwordx4 v220, v[100:103], s[12:13] offset:512
	global_store_dwordx4 v220, v[96:99], s[12:13] offset:528
	v_add_u32_e32 v219, 0x40000, v218
	global_store_dwordx4 v219, v[92:95], s[12:13]
	global_store_dwordx4 v219, v[88:91], s[12:13] offset:16
	global_store_dwordx4 v219, v[84:87], s[12:13] offset:512
	global_store_dwordx4 v219, v[80:83], s[12:13] offset:528
	v_add_u32_e32 v220, 0x60000, v218
	global_store_dwordx4 v220, v[76:79], s[12:13]
	global_store_dwordx4 v220, v[72:75], s[12:13] offset:16
	global_store_dwordx4 v220, v[68:71], s[12:13] offset:512
	global_store_dwordx4 v220, v[64:67], s[12:13] offset:528
	s_waitcnt vmcnt(31)
	v_pk_add_f32 v[60:61], v[60:61], v[144:145]
	v_pk_add_f32 v[62:63], v[62:63], v[146:147]
	s_waitcnt vmcnt(30)
	v_pk_add_f32 v[56:57], v[56:57], v[156:157]
	v_pk_add_f32 v[58:59], v[58:59], v[158:159]
	s_waitcnt vmcnt(29)
	v_pk_add_f32 v[52:53], v[52:53], v[160:161]
	v_pk_add_f32 v[54:55], v[54:55], v[162:163]
	s_waitcnt vmcnt(28)
	v_pk_add_f32 v[48:49], v[48:49], v[164:165]
	v_pk_add_f32 v[50:51], v[50:51], v[166:167]
	s_waitcnt vmcnt(27)
	v_pk_add_f32 v[44:45], v[44:45], v[168:169]
	v_pk_add_f32 v[46:47], v[46:47], v[170:171]
	s_waitcnt vmcnt(26)
	v_pk_add_f32 v[40:41], v[40:41], v[172:173]
	v_pk_add_f32 v[42:43], v[42:43], v[174:175]
	s_waitcnt vmcnt(25)
	v_pk_add_f32 v[36:37], v[36:37], v[176:177]
	v_pk_add_f32 v[38:39], v[38:39], v[178:179]
	s_waitcnt vmcnt(24)
	v_pk_add_f32 v[32:33], v[32:33], v[180:181]
	v_pk_add_f32 v[34:35], v[34:35], v[182:183]
	s_waitcnt vmcnt(23)
	v_pk_add_f32 v[28:29], v[28:29], v[186:187]
	v_pk_add_f32 v[30:31], v[30:31], v[188:189]
	s_waitcnt vmcnt(22)
	v_pk_add_f32 v[24:25], v[24:25], v[190:191]
	v_pk_add_f32 v[26:27], v[26:27], v[192:193]
	s_waitcnt vmcnt(21)
	v_pk_add_f32 v[20:21], v[20:21], v[194:195]
	v_pk_add_f32 v[22:23], v[22:23], v[196:197]
	s_waitcnt vmcnt(20)
	v_pk_add_f32 v[16:17], v[16:17], v[198:199]
	v_pk_add_f32 v[18:19], v[18:19], v[200:201]
	s_waitcnt vmcnt(19)
	v_pk_add_f32 v[12:13], v[12:13], v[202:203]
	v_pk_add_f32 v[14:15], v[14:15], v[204:205]
	s_waitcnt vmcnt(18)
	v_pk_add_f32 v[8:9], v[8:9], v[206:207]
	v_pk_add_f32 v[10:11], v[10:11], v[208:209]
	s_waitcnt vmcnt(17)
	v_pk_add_f32 v[4:5], v[4:5], v[210:211]
	v_pk_add_f32 v[6:7], v[6:7], v[212:213]
	s_waitcnt vmcnt(16)
	v_pk_add_f32 v[0:1], v[0:1], v[214:215]
	v_pk_add_f32 v[2:3], v[2:3], v[216:217]
	v_add_u32_e32 v219, 0x100000, v218
	global_store_dwordx4 v219, v[60:63], s[12:13]
	global_store_dwordx4 v219, v[56:59], s[12:13] offset:16
	global_store_dwordx4 v219, v[52:55], s[12:13] offset:512
	global_store_dwordx4 v219, v[48:51], s[12:13] offset:528
	v_add_u32_e32 v220, 0x120000, v218
	global_store_dwordx4 v220, v[44:47], s[12:13]
	global_store_dwordx4 v220, v[40:43], s[12:13] offset:16
	global_store_dwordx4 v220, v[36:39], s[12:13] offset:512
	global_store_dwordx4 v220, v[32:35], s[12:13] offset:528
	v_add_u32_e32 v219, 0x140000, v218
	global_store_dwordx4 v219, v[28:31], s[12:13]
	global_store_dwordx4 v219, v[24:27], s[12:13] offset:16
	global_store_dwordx4 v219, v[20:23], s[12:13] offset:512
	global_store_dwordx4 v219, v[16:19], s[12:13] offset:528
	v_add_u32_e32 v220, 0x160000, v218
	global_store_dwordx4 v220, v[12:15], s[12:13]
	global_store_dwordx4 v220, v[8:11], s[12:13] offset:16
	global_store_dwordx4 v220, v[4:7], s[12:13] offset:512
	global_store_dwordx4 v220, v[0:3], s[12:13] offset:528
	s_nop 1
	s_cbranch_vccnz .LBB0_1313
	s_andn2_b64 vcc, exec, s[8:9]
	s_cbranch_vccnz .LBB0_1312
	s_barrier
	s_branch .LBB0_1312

;     __device__ __forceinline__ void operator()(const f32x4 (&acc)[2][2][4][2], const Unit& u, int wr, int wc, int fr, int fq) const {
;         const int row0 = u.pm * BM + wr * 64 + fr, col0 = u.pn * BM + wc * 32 + 8 * fq;
; #pragma unroll
;         for (int ai = 0; ai < 2; ++ai)
; #pragma unroll
;             for (int m = 0; m < 4; ++m) { const size_t ro = (size_t)(row0 + ai * HALF + m * 16) * ldc + col0;
; #pragma unroll
;                 for (int bj = 0; bj < 2; ++bj) {
;                     const f32x4 b0 = *(const f32x4*)(base + ro + bj * HALF), b1 = *(const f32x4*)(base + ro + bj * HALF + 4);
;                     *(f32x4*)(out + ro + bj * HALF) = b0 + acc[ai][bj][m][0] * scale;
;                     *(f32x4*)(out + ro + bj * HALF + 4) = b1 + acc[ai][bj][m][1] * scale; } }
.LBB0_1542:
	v_lshl_add_u32 v219, s64, 8, v150
	v_lshl_or_b32 v220, s65, 8, v152
	v_lshlrev_b32_e32 v219, 13, v219
	v_lshl_add_u32 v218, v220, 2, v219
	s_mov_b64 s[40:41], -1
	s_and_b64 vcc, exec, s[4:5]
	v_add_u32_e32 v219, 0x0, v218
	global_load_dwordx4 v[144:147], v219, s[16:17]
	global_load_dwordx4 v[156:159], v219, s[16:17] offset:16
	global_load_dwordx4 v[160:163], v219, s[16:17] offset:512
	global_load_dwordx4 v[164:167], v219, s[16:17] offset:528
	v_add_u32_e32 v220, 0x20000, v218
	global_load_dwordx4 v[168:171], v220, s[16:17]
	global_load_dwordx4 v[172:175], v220, s[16:17] offset:16
	global_load_dwordx4 v[176:179], v220, s[16:17] offset:512
	global_load_dwordx4 v[180:183], v220, s[16:17] offset:528
	v_add_u32_e32 v219, 0x40000, v218
	global_load_dwordx4 v[186:189], v219, s[16:17]
	global_load_dwordx4 v[190:193], v219, s[16:17] offset:16
	global_load_dwordx4 v[194:197], v219, s[16:17] offset:512
	global_load_dwordx4 v[198:201], v219, s[16:17] offset:528
	v_add_u32_e32 v220, 0x60000, v218
	global_load_dwordx4 v[202:205], v220, s[16:17]
	global_load_dwordx4 v[206:209], v220, s[16:17] offset:16
	global_load_dwordx4 v[210:213], v220, s[16:17] offset:512
	global_load_dwordx4 v[214:217], v220, s[16:17] offset:528
	s_waitcnt vmcnt(15)
	v_pk_fma_f32 v[124:125], v[124:125], 0.5, v[144:145] op_sel_hi:[1,0,1]
	v_pk_fma_f32 v[126:127], v[126:127], 0.5, v[146:147] op_sel_hi:[1,0,1]
	s_waitcnt vmcnt(14)
	v_pk_fma_f32 v[120:121], v[120:121], 0.5, v[156:157] op_sel_hi:[1,0,1]
	v_pk_fma_f32 v[122:123], v[122:123], 0.5, v[158:159] op_sel_hi:[1,0,1]
	s_waitcnt vmcnt(13)
	v_pk_fma_f32 v[116:117], v[116:117], 0.5, v[160:161] op_sel_hi:[1,0,1]
	v_pk_fma_f32 v[118:119], v[118:119], 0.5, v[162:163] op_sel_hi:[1,0,1]
	s_waitcnt vmcnt(12)
	v_pk_fma_f32 v[112:113], v[112:113], 0.5, v[164:165] op_sel_hi:[1,0,1]
	v_pk_fma_f32 v[114:115], v[114:115], 0.5, v[166:167] op_sel_hi:[1,0,1]
	s_waitcnt vmcnt(11)
	v_pk_fma_f32 v[108:109], v[108:109], 0.5, v[168:169] op_sel_hi:[1,0,1]
	v_pk_fma_f32 v[110:111], v[110:111], 0.5, v[170:171] op_sel_hi:[1,0,1]
	s_waitcnt vmcnt(10)
	v_pk_fma_f32 v[104:105], v[104:105], 0.5, v[172:173] op_sel_hi:[1,0,1]
	v_pk_fma_f32 v[106:107], v[106:107], 0.5, v[174:175] op_sel_hi:[1,0,1]
	s_waitcnt vmcnt(9)
	v_pk_fma_f32 v[100:101], v[100:101], 0.5, v[176:177] op_sel_hi:[1,0,1]
	v_pk_fma_f32 v[102:103], v[102:103], 0.5, v[178:179] op_sel_hi:[1,0,1]
	s_waitcnt vmcnt(8)
	v_pk_fma_f32 v[96:97], v[96:97], 0.5, v[180:181] op_sel_hi:[1,0,1]
	v_pk_fma_f32 v[98:99], v[98:99], 0.5, v[182:183] op_sel_hi:[1,0,1]
	s_waitcnt vmcnt(7)
	v_pk_fma_f32 v[92:93], v[92:93], 0.5, v[186:187] op_sel_hi:[1,0,1]
	v_pk_fma_f32 v[94:95], v[94:95], 0.5, v[188:189] op_sel_hi:[1,0,1]
	s_waitcnt vmcnt(6)
	v_pk_fma_f32 v[88:89], v[88:89], 0.5, v[190:191] op_sel_hi:[1,0,1]
	v_pk_fma_f32 v[90:91], v[90:91], 0.5, v[192:193] op_sel_hi:[1,0,1]
	s_waitcnt vmcnt(5)
	v_pk_fma_f32 v[84:85], v[84:85], 0.5, v[194:195] op_sel_hi:[1,0,1]
	v_pk_fma_f32 v[86:87], v[86:87], 0.5, v[196:197] op_sel_hi:[1,0,1]
	s_waitcnt vmcnt(4)
	v_pk_fma_f32 v[80:81], v[80:81], 0.5, v[198:199] op_sel_hi:[1,0,1]
	v_pk_fma_f32 v[82:83], v[82:83], 0.5, v[200:201] op_sel_hi:[1,0,1]
	s_waitcnt vmcnt(3)
	v_pk_fma_f32 v[76:77], v[76:77], 0.5, v[202:203] op_sel_hi:[1,0,1]
	v_pk_fma_f32 v[78:79], v[78:79], 0.5, v[204:205] op_sel_hi:[1,0,1]
	s_waitcnt vmcnt(2)
	v_pk_fma_f32 v[72:73], v[72:73], 0.5, v[206:207] op_sel_hi:[1,0,1]
	v_pk_fma_f32 v[74:75], v[74:75], 0.5, v[208:209] op_sel_hi:[1,0,1]
	s_waitcnt vmcnt(1)
	v_pk_fma_f32 v[68:69], v[68:69], 0.5, v[210:211] op_sel_hi:[1,0,1]
	v_pk_fma_f32 v[70:71], v[70:71], 0.5, v[212:213] op_sel_hi:[1,0,1]
	s_waitcnt vmcnt(0)
;     __device__ __forceinline__ void operator()(const f32x4 (&acc)[2][2][4][2], const Unit& u, int wr, int wc, int fr, int fq) const {
;         const int row0 = u.pm * BM + wr * 64 + fr, col0 = u.pn * BM + wc * 32 + 8 * fq;
; #pragma unroll
;         for (int ai = 0; ai < 2; ++ai)
; #pragma unroll
;             for (int m = 0; m < 4; ++m) { const size_t ro = (size_t)(row0 + ai * HALF + m * 16) * ldc + col0;
; #pragma unroll
;                 for (int bj = 0; bj < 2; ++bj) {
;                     const f32x4 b0 = *(const f32x4*)(base + ro + bj * HALF), b1 = *(const f32x4*)(base + ro + bj * HALF + 4);
;                     *(f32x4*)(out + ro + bj * HALF) = b0 + acc[ai][bj][m][0] * scale;
;                     *(f32x4*)(out + ro + bj * HALF + 4) = b1 + acc[ai][bj][m][1] * scale; } }
	v_pk_fma_f32 v[64:65], v[64:65], 0.5, v[214:215] op_sel_hi:[1,0,1]
	v_pk_fma_f32 v[66:67], v[66:67], 0.5, v[216:217] op_sel_hi:[1,0,1]
	v_add_u32_e32 v219, 0x100000, v218
	global_load_dwordx4 v[144:147], v219, s[16:17]
	global_load_dwordx4 v[156:159], v219, s[16:17] offset:16
	global_load_dwordx4 v[160:163], v219, s[16:17] offset:512
	global_load_dwordx4 v[164:167], v219, s[16:17] offset:528
	v_add_u32_e32 v220, 0x120000, v218
	global_load_dwordx4 v[168:171], v220, s[16:17]
	global_load_dwordx4 v[172:175], v220, s[16:17] offset:16
	global_load_dwordx4 v[176:179], v220, s[16:17] offset:512
	global_load_dwordx4 v[180:183], v220, s[16:17] offset:528
	v_add_u32_e32 v219, 0x140000, v218
	global_load_dwordx4 v[186:189], v219, s[16:17]
	global_load_dwordx4 v[190:193], v219, s[16:17] offset:16
	global_load_dwordx4 v[194:197], v219, s[16:17] offset:512
	global_load_dwordx4 v[198:201], v219, s[16:17] offset:528
	v_add_u32_e32 v220, 0x160000, v218
	global_load_dwordx4 v[202:205], v220, s[16:17]
	global_load_dwordx4 v[206:209], v220, s[16:17] offset:16
	global_load_dwordx4 v[210:213], v220, s[16:17] offset:512
	global_load_dwordx4 v[214:217], v220, s[16:17] offset:528
	v_add_u32_e32 v219, 0x0, v218
	global_store_dwordx4 v219, v[124:127], s[16:17]
	global_store_dwordx4 v219, v[120:123], s[16:17] offset:16
	global_store_dwordx4 v219, v[116:119], s[16:17] offset:512
	global_store_dwordx4 v219, v[112:115], s[16:17] offset:528
	v_add_u32_e32 v220, 0x20000, v218
	global_store_dwordx4 v220, v[108:111], s[16:17]
	global_store_dwordx4 v220, v[104:107], s[16:17] offset:16
	global_store_dwordx4 v220, v[100:103], s[16:17] offset:512
	global_store_dwordx4 v220, v[96:99], s[16:17] offset:528
	v_add_u32_e32 v219, 0x40000, v218
	global_store_dwordx4 v219, v[92:95], s[16:17]
	global_store_dwordx4 v219, v[88:91], s[16:17] offset:16
	global_store_dwordx4 v219, v[84:87], s[16:17] offset:512
	global_store_dwordx4 v219, v[80:83], s[16:17] offset:528
	v_add_u32_e32 v220, 0x60000, v218
	global_store_dwordx4 v220, v[76:79], s[16:17]
	global_store_dwordx4 v220, v[72:75], s[16:17] offset:16
	global_store_dwordx4 v220, v[68:71], s[16:17] offset:512
	global_store_dwordx4 v220, v[64:67], s[16:17] offset:528
	s_waitcnt vmcnt(31)
	v_pk_fma_f32 v[60:61], v[60:61], 0.5, v[144:145] op_sel_hi:[1,0,1]
	v_pk_fma_f32 v[62:63], v[62:63], 0.5, v[146:147] op_sel_hi:[1,0,1]
	s_waitcnt vmcnt(30)
	v_pk_fma_f32 v[56:57], v[56:57], 0.5, v[156:157] op_sel_hi:[1,0,1]
	v_pk_fma_f32 v[58:59], v[58:59], 0.5, v[158:159] op_sel_hi:[1,0,1]
	s_waitcnt vmcnt(29)
	v_pk_fma_f32 v[52:53], v[52:53], 0.5, v[160:161] op_sel_hi:[1,0,1]
	v_pk_fma_f32 v[54:55], v[54:55], 0.5, v[162:163] op_sel_hi:[1,0,1]
	s_waitcnt vmcnt(28)
	v_pk_fma_f32 v[48:49], v[48:49], 0.5, v[164:165] op_sel_hi:[1,0,1]
	v_pk_fma_f32 v[50:51], v[50:51], 0.5, v[166:167] op_sel_hi:[1,0,1]
	s_waitcnt vmcnt(27)
	v_pk_fma_f32 v[44:45], v[44:45], 0.5, v[168:169] op_sel_hi:[1,0,1]
	v_pk_fma_f32 v[46:47], v[46:47], 0.5, v[170:171] op_sel_hi:[1,0,1]
	s_waitcnt vmcnt(26)
	v_pk_fma_f32 v[40:41], v[40:41], 0.5, v[172:173] op_sel_hi:[1,0,1]
	v_pk_fma_f32 v[42:43], v[42:43], 0.5, v[174:175] op_sel_hi:[1,0,1]
	s_waitcnt vmcnt(25)
	v_pk_fma_f32 v[36:37], v[36:37], 0.5, v[176:177] op_sel_hi:[1,0,1]
	v_pk_fma_f32 v[38:39], v[38:39], 0.5, v[178:179] op_sel_hi:[1,0,1]
	s_waitcnt vmcnt(24)
	v_pk_fma_f32 v[32:33], v[32:33], 0.5, v[180:181] op_sel_hi:[1,0,1]
	v_pk_fma_f32 v[34:35], v[34:35], 0.5, v[182:183] op_sel_hi:[1,0,1]
	s_waitcnt vmcnt(23)
	v_pk_fma_f32 v[28:29], v[28:29], 0.5, v[186:187] op_sel_hi:[1,0,1]
	v_pk_fma_f32 v[30:31], v[30:31], 0.5, v[188:189] op_sel_hi:[1,0,1]
	s_waitcnt vmcnt(22)
	v_pk_fma_f32 v[24:25], v[24:25], 0.5, v[190:191] op_sel_hi:[1,0,1]
	v_pk_fma_f32 v[26:27], v[26:27], 0.5, v[192:193] op_sel_hi:[1,0,1]
	s_waitcnt vmcnt(21)
	v_pk_fma_f32 v[20:21], v[20:21], 0.5, v[194:195] op_sel_hi:[1,0,1]
	v_pk_fma_f32 v[22:23], v[22:23], 0.5, v[196:197] op_sel_hi:[1,0,1]
	s_waitcnt vmcnt(20)
	v_pk_fma_f32 v[16:17], v[16:17], 0.5, v[198:199] op_sel_hi:[1,0,1]
	v_pk_fma_f32 v[18:19], v[18:19], 0.5, v[200:201] op_sel_hi:[1,0,1]
	s_waitcnt vmcnt(19)
	v_pk_fma_f32 v[12:13], v[12:13], 0.5, v[202:203] op_sel_hi:[1,0,1]
	v_pk_fma_f32 v[14:15], v[14:15], 0.5, v[204:205] op_sel_hi:[1,0,1]
	s_waitcnt vmcnt(18)
	v_pk_fma_f32 v[8:9], v[8:9], 0.5, v[206:207] op_sel_hi:[1,0,1]
	v_pk_fma_f32 v[10:11], v[10:11], 0.5, v[208:209] op_sel_hi:[1,0,1]
	s_waitcnt vmcnt(17)
	v_pk_fma_f32 v[4:5], v[4:5], 0.5, v[210:211] op_sel_hi:[1,0,1]
	v_pk_fma_f32 v[6:7], v[6:7], 0.5, v[212:213] op_sel_hi:[1,0,1]
	s_waitcnt vmcnt(16)
	v_pk_fma_f32 v[0:1], v[0:1], 0.5, v[214:215] op_sel_hi:[1,0,1]
	v_pk_fma_f32 v[2:3], v[2:3], 0.5, v[216:217] op_sel_hi:[1,0,1]
	v_add_u32_e32 v219, 0x100000, v218
	global_store_dwordx4 v219, v[60:63], s[16:17]
	global_store_dwordx4 v219, v[56:59], s[16:17] offset:16
	global_store_dwordx4 v219, v[52:55], s[16:17] offset:512
	global_store_dwordx4 v219, v[48:51], s[16:17] offset:528
	v_add_u32_e32 v220, 0x120000, v218
	global_store_dwordx4 v220, v[44:47], s[16:17]
	global_store_dwordx4 v220, v[40:43], s[16:17] offset:16
	global_store_dwordx4 v220, v[36:39], s[16:17] offset:512
	global_store_dwordx4 v220, v[32:35], s[16:17] offset:528
	v_add_u32_e32 v219, 0x140000, v218
	global_store_dwordx4 v219, v[28:31], s[16:17]
	global_store_dwordx4 v219, v[24:27], s[16:17] offset:16
	global_store_dwordx4 v219, v[20:23], s[16:17] offset:512
	global_store_dwordx4 v219, v[16:19], s[16:17] offset:528
	v_add_u32_e32 v220, 0x160000, v218
	global_store_dwordx4 v220, v[12:15], s[16:17]
	global_store_dwordx4 v220, v[8:11], s[16:17] offset:16
	global_store_dwordx4 v220, v[4:7], s[16:17] offset:512
	global_store_dwordx4 v220, v[0:3], s[16:17] offset:528
	s_nop 1
	s_cbranch_vccnz .LBB0_1527
	s_andn2_b64 vcc, exec, s[12:13]
	s_cbranch_vccnz .LBB0_1526
	s_barrier
	s_branch .LBB0_1526
